# first K iteration of both GEMM K-loops peeled: first-touch MFMAs take C=0, accumulator zeroing removed
# speedup vs baseline: 1.0148x; 1.0098x over previous
_Z6mk_fwd4Args:
	s_mov_b32 s46, s2
	s_mov_b32 s100, 0
	s_add_u32 s2, s0, 0xa8
	s_addc_u32 s3, s1, 0
	v_and_b32_e32 v210, 0x3ff, v0
	v_writelane_b32 v252, s2, 0
	v_cmp_gt_u32_e32 vcc, 2, v210
	s_nop 0
	v_writelane_b32 v252, s3, 1
	s_and_saveexec_b64 s[2:3], vcc
	v_lshl_add_u32 v1, v210, 2, 0
	v_add_u32_e32 v1, 0x25400, v1
	v_mov_b32_e32 v2, 0
	ds_write_b32 v1, v2
	s_or_b64 exec, exec, s[2:3]
	s_load_dwordx2 s[48:49], s[0:1], 0xa8
	s_waitcnt lgkmcnt(0)
	s_barrier
	s_load_dword s2, s[0:1], 0xa4
	s_load_dword s3, s[0:1], 0xa0
	v_cmp_eq_u32_e32 vcc, 0, v210
	s_waitcnt lgkmcnt(0)
	s_sub_i32 s2, s2, s3
	s_cmp_lt_i32 s2, 2
	s_cbranch_scc1 .LBB0_8
	s_load_dwordx2 s[4:5], s[0:1], 0x98
	s_getreg_b32 s2, hwreg(HW_REG_XCC_ID, 0, 4)
	s_and_b32 s10, s2, 15
	s_waitcnt lgkmcnt(0)
	v_mov_b64_e32 v[174:175], s[4:5]
	s_and_saveexec_b64 s[2:3], vcc
	s_cbranch_execz .LBB0_7
	s_mov_b64 s[8:9], exec
	v_mbcnt_lo_u32_b32 v1, s8, 0
	v_mbcnt_hi_u32_b32 v1, s9, v1
	v_cmp_eq_u32_e32 vcc, 0, v1
	v_mov_b64_e32 v[174:175], s[4:5]
	s_and_saveexec_b64 s[6:7], vcc
	s_cbranch_execz .LBB0_6
	s_lshl_b32 s11, s10, 8
	s_bcnt1_i32_b64 s8, s[8:9]
	v_mov_b32_e32 v1, s11
	v_mov_b32_e32 v2, s8
	global_atomic_add v1, v2, s[4:5] offset:1024
	v_mov_b64_e32 v[174:175], s[4:5]

.LBB0_404:
	s_ashr_i32 s55, s54, 31
	s_lshl_b64 s[2:3], s[54:55], 19
	s_add_u32 s56, s60, s2
	s_addc_u32 s57, s65, s3
	s_and_b64 s[2:3], s[10:11], exec
	s_cselect_b32 s16, s57, s15
	s_cselect_b32 s17, s56, s14
	s_ashr_i32 s31, s30, 31
	s_lshl_b64 s[2:3], s[30:31], 19
	s_add_u32 s4, s66, s2
	s_addc_u32 s5, s68, s3
	s_and_b64 s[2:3], s[10:11], exec
	s_cselect_b32 s18, s5, s13
	s_cselect_b32 s19, s4, s12
	s_add_u32 s2, s14, 0x40080
	s_addc_u32 s3, s15, 0
	s_add_u32 s20, s12, 0x100
	s_addc_u32 s21, s13, 0
	s_mov_b32 s22, -2
	s_add_u32 s12, s2, 0xfffc0080
	s_addc_u32 s13, s3, -1
	s_add_i32 s23, 0, 0x10000
	s_cmp_eq_u32 s22, 12
	s_cselect_b32 s15, s16, s13
	s_cselect_b32 s14, s17, s12
	v_add_u32_e32 v96, s23, v221
	s_cselect_b32 s13, s18, s21
	s_cselect_b32 s12, s19, s20
	s_add_i32 s31, 0, 0x14000
	ds_read_b128 v[0:3], v96
	ds_read_b128 v[4:7], v96 offset:1024
	ds_read_b128 v[138:141], v96 offset:2048
	ds_read_b128 v[142:145], v96 offset:3072
	v_add_u32_e32 v96, s31, v221
	ds_read_b128 v[146:149], v96
	ds_read_b128 v[150:153], v96 offset:1024
	ds_read_b128 v[180:183], v96 offset:2048
	ds_read_b128 v[184:187], v96 offset:3072
	v_lshl_add_u64 v[170:171], s[2:3], 0, v[166:167]
	s_add_i32 m0, s69, 0xc000
	ds_read_b128 v[188:191], v231
	ds_read_b128 v[192:195], v231 offset:1024
	ds_read_b128 v[196:199], v231 offset:2048
	ds_read_b128 v[200:203], v231 offset:3072
	ds_read_b128 v[204:207], v231 offset:4096
	ds_read_b128 v[234:237], v231 offset:5120
	ds_read_b128 v[238:241], v231 offset:6144
	ds_read_b128 v[242:245], v231 offset:7168
	global_load_lds_dwordx4 v[170:171], off
	v_lshl_add_u64 v[170:171], s[2:3], 0, v[168:169]
	s_add_i32 m0, s69, 0xe000
	s_nop 0
	global_load_lds_dwordx4 v[170:171], off
	s_waitcnt vmcnt(8)
	s_waitcnt lgkmcnt(0)
	s_barrier
	s_setprio 1
	s_waitcnt lgkmcnt(0)
	v_mfma_f32_16x16x32_bf16 v[134:137], v[0:3], v[188:191], 0
	v_mfma_f32_16x16x32_bf16 v[130:133], v[138:141], v[188:191], 0
	v_mfma_f32_16x16x32_bf16 v[118:121], v[0:3], v[196:199], 0
	v_mfma_f32_16x16x32_bf16 v[114:117], v[138:141], v[196:199], 0
	v_mfma_f32_16x16x32_bf16 v[102:105], v[0:3], v[204:207], 0
	v_mfma_f32_16x16x32_bf16 v[98:101], v[138:141], v[204:207], 0
	v_mfma_f32_16x16x32_bf16 v[84:87], v[0:3], v[238:241], 0
	v_mfma_f32_16x16x32_bf16 v[80:83], v[138:141], v[238:241], 0
	v_mfma_f32_16x16x32_bf16 v[134:137], v[4:7], v[192:195], v[134:137]
	v_mfma_f32_16x16x32_bf16 v[130:133], v[142:145], v[192:195], v[130:133]
	v_mfma_f32_16x16x32_bf16 v[118:121], v[4:7], v[200:203], v[118:121]
	v_mfma_f32_16x16x32_bf16 v[114:117], v[142:145], v[200:203], v[114:117]
	v_mfma_f32_16x16x32_bf16 v[102:105], v[4:7], v[234:237], v[102:105]
	v_mfma_f32_16x16x32_bf16 v[98:101], v[142:145], v[234:237], v[98:101]
	v_mfma_f32_16x16x32_bf16 v[84:87], v[4:7], v[242:245], v[84:87]
	v_mfma_f32_16x16x32_bf16 v[80:83], v[142:145], v[242:245], v[80:83]
	s_setprio 0
	s_setprio 1
	v_mfma_f32_16x16x32_bf16 v[126:129], v[146:149], v[188:191], 0
	v_mfma_f32_16x16x32_bf16 v[122:125], v[180:183], v[188:191], 0
	v_mfma_f32_16x16x32_bf16 v[110:113], v[146:149], v[196:199], 0
	v_mfma_f32_16x16x32_bf16 v[106:109], v[180:183], v[196:199], 0
	v_mfma_f32_16x16x32_bf16 v[92:95], v[146:149], v[204:207], 0
	v_mfma_f32_16x16x32_bf16 v[88:91], v[180:183], v[204:207], 0
	v_mfma_f32_16x16x32_bf16 v[76:79], v[146:149], v[238:241], 0
	v_mfma_f32_16x16x32_bf16 v[72:75], v[180:183], v[238:241], 0
	v_mfma_f32_16x16x32_bf16 v[126:129], v[150:153], v[192:195], v[126:129]
	v_mfma_f32_16x16x32_bf16 v[122:125], v[184:187], v[192:195], v[122:125]
	v_mfma_f32_16x16x32_bf16 v[110:113], v[150:153], v[200:203], v[110:113]
	v_mfma_f32_16x16x32_bf16 v[106:109], v[184:187], v[200:203], v[106:109]
	v_mfma_f32_16x16x32_bf16 v[92:95], v[150:153], v[234:237], v[92:95]
	v_mfma_f32_16x16x32_bf16 v[88:91], v[184:187], v[234:237], v[88:91]
	v_mfma_f32_16x16x32_bf16 v[76:79], v[150:153], v[242:245], v[76:79]
	v_mfma_f32_16x16x32_bf16 v[72:75], v[184:187], v[242:245], v[72:75]
	s_setprio 0
	s_barrier
	s_add_i32 s23, s23, s58
	v_lshl_add_u64 v[170:171], s[12:13], 0, v[156:157]
	s_mov_b32 m0, s23
	ds_read_b128 v[188:191], v231 offset:16384
	ds_read_b128 v[192:195], v231 offset:17408
	ds_read_b128 v[196:199], v231 offset:18432
	ds_read_b128 v[200:203], v231 offset:19456
	ds_read_b128 v[204:207], v231 offset:20480
	ds_read_b128 v[234:237], v231 offset:21504
	ds_read_b128 v[238:241], v231 offset:22528
	ds_read_b128 v[242:245], v231 offset:23552
	global_load_lds_dwordx4 v[170:171], off
	s_add_i32 m0, s23, 0x2000
	s_add_u32 s26, s12, 0x10000
	v_lshl_add_u64 v[208:209], s[12:13], 0, v[160:161]
	s_addc_u32 s27, s13, 0
	s_add_i32 s23, s31, s58
	global_load_lds_dwordx4 v[208:209], off
	v_lshl_add_u64 v[246:247], s[26:27], 0, v[156:157]
	s_mov_b32 m0, s23
	v_lshl_add_u64 v[248:249], s[14:15], 0, v[158:159]
	global_load_lds_dwordx4 v[246:247], off
	v_lshl_add_u64 v[246:247], s[26:27], 0, v[160:161]
	s_add_i32 m0, s23, 0x2000
	s_nop 0
	global_load_lds_dwordx4 v[246:247], off
	v_lshl_add_u64 v[246:247], s[14:15], 0, v[154:155]
	s_mov_b32 m0, s69
	s_nop 0
	global_load_lds_dwordx4 v[246:247], off
	s_mov_b32 m0, s70
	s_nop 0
	global_load_lds_dwordx4 v[248:249], off
	s_waitcnt vmcnt(8)
	s_waitcnt lgkmcnt(0)
	s_barrier
	s_setprio 1
	s_waitcnt lgkmcnt(0)
	v_mfma_f32_16x16x32_bf16 v[68:71], v[0:3], v[188:191], 0
	v_mfma_f32_16x16x32_bf16 v[64:67], v[138:141], v[188:191], 0
	v_mfma_f32_16x16x32_bf16 v[52:55], v[0:3], v[196:199], 0
	v_mfma_f32_16x16x32_bf16 v[48:51], v[138:141], v[196:199], 0
	v_mfma_f32_16x16x32_bf16 v[36:39], v[0:3], v[204:207], 0
	v_mfma_f32_16x16x32_bf16 v[32:35], v[138:141], v[204:207], 0
	v_mfma_f32_16x16x32_bf16 v[0:3], v[0:3], v[238:241], 0
	v_mfma_f32_16x16x32_bf16 v[68:71], v[4:7], v[192:195], v[68:71]
	v_mfma_f32_16x16x32_bf16 v[64:67], v[142:145], v[192:195], v[64:67]
	v_mfma_f32_16x16x32_bf16 v[52:55], v[4:7], v[200:203], v[52:55]
	v_mfma_f32_16x16x32_bf16 v[48:51], v[142:145], v[200:203], v[48:51]
	v_mfma_f32_16x16x32_bf16 v[36:39], v[4:7], v[234:237], v[36:39]
	v_mfma_f32_16x16x32_bf16 v[32:35], v[142:145], v[234:237], v[32:35]
	v_mfma_f32_16x16x32_bf16 v[0:3], v[4:7], v[242:245], v[0:3]
	v_mfma_f32_16x16x32_bf16 v[4:7], v[138:141], v[238:241], 0
	v_mfma_f32_16x16x32_bf16 v[4:7], v[142:145], v[242:245], v[4:7]
	s_setprio 0
	s_setprio 1
	v_mfma_f32_16x16x32_bf16 v[16:19], v[146:149], v[188:191], 0
	v_mfma_f32_16x16x32_bf16 v[60:63], v[150:153], v[192:195], v[16:19]
	v_mfma_f32_16x16x32_bf16 v[16:19], v[180:183], v[188:191], 0
	v_mfma_f32_16x16x32_bf16 v[56:59], v[184:187], v[192:195], v[16:19]
	v_mfma_f32_16x16x32_bf16 v[16:19], v[146:149], v[196:199], 0
	v_mfma_f32_16x16x32_bf16 v[44:47], v[150:153], v[200:203], v[16:19]
	v_mfma_f32_16x16x32_bf16 v[16:19], v[180:183], v[196:199], 0
	v_mfma_f32_16x16x32_bf16 v[40:43], v[184:187], v[200:203], v[16:19]
	v_mfma_f32_16x16x32_bf16 v[16:19], v[146:149], v[204:207], 0
	v_mfma_f32_16x16x32_bf16 v[28:31], v[150:153], v[234:237], v[16:19]
	v_mfma_f32_16x16x32_bf16 v[16:19], v[180:183], v[204:207], 0
	v_mfma_f32_16x16x32_bf16 v[12:15], v[146:149], v[238:241], 0
	v_mfma_f32_16x16x32_bf16 v[8:11], v[180:183], v[238:241], 0
	v_mfma_f32_16x16x32_bf16 v[24:27], v[184:187], v[234:237], v[16:19]
	v_mfma_f32_16x16x32_bf16 v[12:15], v[150:153], v[242:245], v[12:15]
	v_mfma_f32_16x16x32_bf16 v[8:11], v[184:187], v[242:245], v[8:11]
	s_setprio 0
	s_barrier
	v_add_u32_e32 v96, s67, v221
	s_add_i32 s23, 0, 0x1c000
	ds_read_b128 v[16:19], v96
	ds_read_b128 v[20:23], v96 offset:1024
	ds_read_b128 v[138:141], v96 offset:2048
	ds_read_b128 v[142:145], v96 offset:3072
	v_add_u32_e32 v96, s23, v221
	ds_read_b128 v[146:149], v96
	ds_read_b128 v[150:153], v96 offset:1024
	ds_read_b128 v[180:183], v96 offset:2048
	ds_read_b128 v[184:187], v96 offset:3072
	s_add_u32 s14, s14, 0x40000
	s_addc_u32 s15, s15, 0
	s_mov_b32 m0, s71
	v_lshl_add_u64 v[250:251], s[14:15], 0, v[154:155]
	ds_read_b128 v[188:191], v231 offset:32768
	ds_read_b128 v[192:195], v231 offset:33792
	ds_read_b128 v[196:199], v231 offset:34816
	ds_read_b128 v[200:203], v231 offset:35840
	ds_read_b128 v[204:207], v231 offset:36864
	ds_read_b128 v[234:237], v231 offset:37888
	ds_read_b128 v[238:241], v231 offset:38912
	ds_read_b128 v[242:245], v231 offset:39936
	global_load_lds_dwordx4 v[250:251], off
	v_lshl_add_u64 v[250:251], s[14:15], 0, v[158:159]
	s_mov_b32 m0, s76
	s_nop 0
	global_load_lds_dwordx4 v[250:251], off
	s_waitcnt vmcnt(8)
	s_waitcnt lgkmcnt(0)
	s_barrier
	s_setprio 1
	s_waitcnt lgkmcnt(0)
	v_mfma_f32_16x16x32_bf16 v[134:137], v[16:19], v[188:191], v[134:137]
	v_mfma_f32_16x16x32_bf16 v[130:133], v[138:141], v[188:191], v[130:133]
	v_mfma_f32_16x16x32_bf16 v[118:121], v[16:19], v[196:199], v[118:121]
	v_mfma_f32_16x16x32_bf16 v[114:117], v[138:141], v[196:199], v[114:117]
	v_mfma_f32_16x16x32_bf16 v[102:105], v[16:19], v[204:207], v[102:105]
	v_mfma_f32_16x16x32_bf16 v[98:101], v[138:141], v[204:207], v[98:101]
	v_mfma_f32_16x16x32_bf16 v[84:87], v[16:19], v[238:241], v[84:87]
	v_mfma_f32_16x16x32_bf16 v[80:83], v[138:141], v[238:241], v[80:83]
	v_mfma_f32_16x16x32_bf16 v[134:137], v[20:23], v[192:195], v[134:137]
	v_mfma_f32_16x16x32_bf16 v[130:133], v[142:145], v[192:195], v[130:133]
	v_mfma_f32_16x16x32_bf16 v[118:121], v[20:23], v[200:203], v[118:121]
	v_mfma_f32_16x16x32_bf16 v[114:117], v[142:145], v[200:203], v[114:117]
	v_mfma_f32_16x16x32_bf16 v[102:105], v[20:23], v[234:237], v[102:105]
	v_mfma_f32_16x16x32_bf16 v[98:101], v[142:145], v[234:237], v[98:101]
	v_mfma_f32_16x16x32_bf16 v[84:87], v[20:23], v[242:245], v[84:87]
	v_mfma_f32_16x16x32_bf16 v[80:83], v[142:145], v[242:245], v[80:83]
	s_setprio 0
	s_setprio 1
	v_mfma_f32_16x16x32_bf16 v[126:129], v[146:149], v[188:191], v[126:129]
	v_mfma_f32_16x16x32_bf16 v[122:125], v[180:183], v[188:191], v[122:125]
	v_mfma_f32_16x16x32_bf16 v[110:113], v[146:149], v[196:199], v[110:113]
	v_mfma_f32_16x16x32_bf16 v[106:109], v[180:183], v[196:199], v[106:109]
	v_mfma_f32_16x16x32_bf16 v[92:95], v[146:149], v[204:207], v[92:95]
	v_mfma_f32_16x16x32_bf16 v[88:91], v[180:183], v[204:207], v[88:91]
	v_mfma_f32_16x16x32_bf16 v[76:79], v[146:149], v[238:241], v[76:79]
	v_mfma_f32_16x16x32_bf16 v[72:75], v[180:183], v[238:241], v[72:75]
	v_mfma_f32_16x16x32_bf16 v[126:129], v[150:153], v[192:195], v[126:129]
	v_mfma_f32_16x16x32_bf16 v[122:125], v[184:187], v[192:195], v[122:125]
	v_mfma_f32_16x16x32_bf16 v[110:113], v[150:153], v[200:203], v[110:113]
	v_mfma_f32_16x16x32_bf16 v[106:109], v[184:187], v[200:203], v[106:109]
	v_mfma_f32_16x16x32_bf16 v[92:95], v[150:153], v[234:237], v[92:95]
	v_mfma_f32_16x16x32_bf16 v[88:91], v[184:187], v[234:237], v[88:91]
	v_mfma_f32_16x16x32_bf16 v[76:79], v[150:153], v[242:245], v[76:79]
	v_mfma_f32_16x16x32_bf16 v[72:75], v[184:187], v[242:245], v[72:75]
	s_setprio 0
	s_barrier
	s_add_i32 s14, s67, s58
	v_lshl_add_u64 v[170:171], v[170:171], 0, s[62:63]
	s_mov_b32 m0, s14
	ds_read_b128 v[188:191], v231 offset:49152
	ds_read_b128 v[192:195], v231 offset:50176
	ds_read_b128 v[196:199], v231 offset:51200
	ds_read_b128 v[200:203], v231 offset:52224
	ds_read_b128 v[204:207], v231 offset:53248
	ds_read_b128 v[234:237], v231 offset:54272
	ds_read_b128 v[238:241], v231 offset:55296
	ds_read_b128 v[242:245], v231 offset:56320
	global_load_lds_dwordx4 v[170:171], off
	s_add_i32 m0, s14, 0x2000
	s_add_u32 s12, s12, 0x10080
	v_lshl_add_u64 v[170:171], v[208:209], 0, s[62:63]
	s_addc_u32 s13, s13, 0
	s_add_i32 s14, s23, s58
	global_load_lds_dwordx4 v[170:171], off
	v_lshl_add_u64 v[170:171], s[12:13], 0, v[156:157]
	s_mov_b32 m0, s14
	s_nop 0
	global_load_lds_dwordx4 v[170:171], off
	v_lshl_add_u64 v[170:171], s[12:13], 0, v[160:161]
	s_add_i32 m0, s14, 0x2000
	s_nop 0
	global_load_lds_dwordx4 v[170:171], off
	v_lshl_add_u64 v[170:171], v[246:247], 0, s[62:63]
	s_mov_b32 m0, s96
	s_nop 0
	global_load_lds_dwordx4 v[170:171], off
	v_lshl_add_u64 v[170:171], v[248:249], 0, s[62:63]
	s_mov_b32 m0, s36
	s_nop 0
	global_load_lds_dwordx4 v[170:171], off
	s_waitcnt vmcnt(8)
	s_waitcnt lgkmcnt(0)
	s_barrier
	s_setprio 1
	s_waitcnt lgkmcnt(0)
	v_mfma_f32_16x16x32_bf16 v[68:71], v[16:19], v[188:191], v[68:71]
	v_mfma_f32_16x16x32_bf16 v[52:55], v[16:19], v[196:199], v[52:55]
	v_mfma_f32_16x16x32_bf16 v[36:39], v[16:19], v[204:207], v[36:39]
	v_mfma_f32_16x16x32_bf16 v[0:3], v[16:19], v[238:241], v[0:3]
	v_mfma_f32_16x16x32_bf16 v[68:71], v[20:23], v[192:195], v[68:71]
	v_mfma_f32_16x16x32_bf16 v[64:67], v[138:141], v[188:191], v[64:67]
	v_mfma_f32_16x16x32_bf16 v[52:55], v[20:23], v[200:203], v[52:55]
	v_mfma_f32_16x16x32_bf16 v[48:51], v[138:141], v[196:199], v[48:51]
	v_mfma_f32_16x16x32_bf16 v[36:39], v[20:23], v[234:237], v[36:39]
	v_mfma_f32_16x16x32_bf16 v[32:35], v[138:141], v[204:207], v[32:35]
	v_mfma_f32_16x16x32_bf16 v[20:23], v[20:23], v[242:245], v[0:3]
	v_mfma_f32_16x16x32_bf16 v[0:3], v[138:141], v[238:241], v[4:7]
	v_mfma_f32_16x16x32_bf16 v[64:67], v[142:145], v[192:195], v[64:67]
	v_mfma_f32_16x16x32_bf16 v[48:51], v[142:145], v[200:203], v[48:51]
	v_mfma_f32_16x16x32_bf16 v[32:35], v[142:145], v[234:237], v[32:35]
	v_mfma_f32_16x16x32_bf16 v[16:19], v[142:145], v[242:245], v[0:3]
	s_setprio 0
	s_setprio 1
	v_mfma_f32_16x16x32_bf16 v[0:3], v[146:149], v[188:191], v[60:63]
	v_mfma_f32_16x16x32_bf16 v[60:63], v[150:153], v[192:195], v[0:3]
	v_mfma_f32_16x16x32_bf16 v[0:3], v[180:183], v[188:191], v[56:59]
	v_mfma_f32_16x16x32_bf16 v[56:59], v[184:187], v[192:195], v[0:3]
	v_mfma_f32_16x16x32_bf16 v[0:3], v[146:149], v[196:199], v[44:47]
	v_mfma_f32_16x16x32_bf16 v[44:47], v[150:153], v[200:203], v[0:3]
	v_mfma_f32_16x16x32_bf16 v[0:3], v[180:183], v[196:199], v[40:43]
	v_mfma_f32_16x16x32_bf16 v[40:43], v[184:187], v[200:203], v[0:3]
	v_mfma_f32_16x16x32_bf16 v[0:3], v[146:149], v[204:207], v[28:31]
	v_mfma_f32_16x16x32_bf16 v[28:31], v[150:153], v[234:237], v[0:3]
	v_mfma_f32_16x16x32_bf16 v[0:3], v[180:183], v[204:207], v[24:27]
	v_mfma_f32_16x16x32_bf16 v[24:27], v[184:187], v[234:237], v[0:3]
	v_mfma_f32_16x16x32_bf16 v[0:3], v[146:149], v[238:241], v[12:15]
	v_mfma_f32_16x16x32_bf16 v[12:15], v[150:153], v[242:245], v[0:3]
	v_mfma_f32_16x16x32_bf16 v[0:3], v[180:183], v[238:241], v[8:11]
	v_mfma_f32_16x16x32_bf16 v[8:11], v[184:187], v[242:245], v[0:3]
	s_setprio 0
	s_barrier
	s_add_i32 s22, s22, 2
	s_add_u32 s2, s2, 0x100
	s_addc_u32 s3, s3, 0
	s_add_u32 s20, s20, 0x100
	s_addc_u32 s21, s21, 0
	.p2align 6

.LBB0_749:
	s_ashr_i32 s49, s48, 31
	s_waitcnt lgkmcnt(0)
	s_lshl_b64 s[14:15], s[48:49], 19
	s_add_u32 s38, s22, s14
	s_addc_u32 s39, s23, s15
	s_and_b64 s[14:15], s[8:9], exec
	s_cselect_b32 s3, s39, s5
	s_cselect_b32 s16, s38, s4
	s_ashr_i32 s35, s34, 31
	s_lshl_b64 s[14:15], s[34:35], 19
	s_add_u32 s40, s56, s14
	s_addc_u32 s41, s57, s15
	s_and_b64 s[14:15], s[8:9], exec
	s_cselect_b32 s17, s41, s13
	s_cselect_b32 s18, s40, s12
	s_add_u32 s4, s4, 0x40080
	s_addc_u32 s5, s5, 0
	s_add_u32 s19, s12, 0x100
	s_addc_u32 s26, s13, 0
	s_mov_b32 s27, -2
	s_add_u32 s12, s4, 0xfffc0080
	s_addc_u32 s13, s5, -1
	s_add_i32 s33, 0, 0x10000
	s_cmp_eq_u32 s27, 12
	s_cselect_b32 s15, s3, s13
	s_cselect_b32 s14, s16, s12
	v_add_u32_e32 v96, s33, v165
	s_cselect_b32 s13, s17, s26
	s_cselect_b32 s12, s18, s19
	s_add_i32 s35, 0, 0x14000
	ds_read_b128 v[0:3], v96
	ds_read_b128 v[4:7], v96 offset:1024
	ds_read_b128 v[138:141], v96 offset:2048
	ds_read_b128 v[142:145], v96 offset:3072
	v_add_u32_e32 v96, s35, v165
	ds_read_b128 v[146:149], v96
	ds_read_b128 v[150:153], v96 offset:1024
	ds_read_b128 v[182:185], v96 offset:2048
	ds_read_b128 v[186:189], v96 offset:3072
	v_lshl_add_u64 v[238:239], s[4:5], 0, v[168:169]
	s_add_i32 m0, s79, 0xc000
	ds_read_b128 v[190:193], v221
	ds_read_b128 v[194:197], v221 offset:1024
	ds_read_b128 v[198:201], v221 offset:2048
	ds_read_b128 v[202:205], v221 offset:3072
	ds_read_b128 v[222:225], v221 offset:4096
	ds_read_b128 v[226:229], v221 offset:5120
	ds_read_b128 v[230:233], v221 offset:6144
	ds_read_b128 v[234:237], v221 offset:7168
	global_load_lds_dwordx4 v[238:239], off
	v_lshl_add_u64 v[238:239], s[4:5], 0, v[170:171]
	s_add_i32 m0, s79, 0xe000
	s_nop 0
	global_load_lds_dwordx4 v[238:239], off
	s_waitcnt vmcnt(8)
	s_waitcnt lgkmcnt(0)
	s_barrier
	s_setprio 1
	s_waitcnt lgkmcnt(0)
	v_mfma_f32_16x16x32_bf16 v[134:137], v[0:3], v[190:193], 0
	v_mfma_f32_16x16x32_bf16 v[130:133], v[138:141], v[190:193], 0
	v_mfma_f32_16x16x32_bf16 v[118:121], v[0:3], v[198:201], 0
	v_mfma_f32_16x16x32_bf16 v[114:117], v[138:141], v[198:201], 0
	v_mfma_f32_16x16x32_bf16 v[102:105], v[0:3], v[222:225], 0
	v_mfma_f32_16x16x32_bf16 v[98:101], v[138:141], v[222:225], 0
	v_mfma_f32_16x16x32_bf16 v[84:87], v[0:3], v[230:233], 0
	v_mfma_f32_16x16x32_bf16 v[80:83], v[138:141], v[230:233], 0
	v_mfma_f32_16x16x32_bf16 v[134:137], v[4:7], v[194:197], v[134:137]
	v_mfma_f32_16x16x32_bf16 v[130:133], v[142:145], v[194:197], v[130:133]
	v_mfma_f32_16x16x32_bf16 v[118:121], v[4:7], v[202:205], v[118:121]
	v_mfma_f32_16x16x32_bf16 v[114:117], v[142:145], v[202:205], v[114:117]
	v_mfma_f32_16x16x32_bf16 v[102:105], v[4:7], v[226:229], v[102:105]
	v_mfma_f32_16x16x32_bf16 v[98:101], v[142:145], v[226:229], v[98:101]
	v_mfma_f32_16x16x32_bf16 v[84:87], v[4:7], v[234:237], v[84:87]
	v_mfma_f32_16x16x32_bf16 v[80:83], v[142:145], v[234:237], v[80:83]
	s_setprio 0
	s_setprio 1
	v_mfma_f32_16x16x32_bf16 v[126:129], v[146:149], v[190:193], 0
	v_mfma_f32_16x16x32_bf16 v[122:125], v[182:185], v[190:193], 0
	v_mfma_f32_16x16x32_bf16 v[110:113], v[146:149], v[198:201], 0
	v_mfma_f32_16x16x32_bf16 v[106:109], v[182:185], v[198:201], 0
	v_mfma_f32_16x16x32_bf16 v[92:95], v[146:149], v[222:225], 0
	v_mfma_f32_16x16x32_bf16 v[88:91], v[182:185], v[222:225], 0
	v_mfma_f32_16x16x32_bf16 v[76:79], v[146:149], v[230:233], 0
	v_mfma_f32_16x16x32_bf16 v[72:75], v[182:185], v[230:233], 0
	v_mfma_f32_16x16x32_bf16 v[126:129], v[150:153], v[194:197], v[126:129]
	v_mfma_f32_16x16x32_bf16 v[122:125], v[186:189], v[194:197], v[122:125]
	v_mfma_f32_16x16x32_bf16 v[110:113], v[150:153], v[202:205], v[110:113]
	v_mfma_f32_16x16x32_bf16 v[106:109], v[186:189], v[202:205], v[106:109]
	v_mfma_f32_16x16x32_bf16 v[92:95], v[150:153], v[226:229], v[92:95]
	v_mfma_f32_16x16x32_bf16 v[88:91], v[186:189], v[226:229], v[88:91]
	v_mfma_f32_16x16x32_bf16 v[76:79], v[150:153], v[234:237], v[76:79]
	v_mfma_f32_16x16x32_bf16 v[72:75], v[186:189], v[234:237], v[72:75]
	s_setprio 0
	s_barrier
	s_add_i32 s33, s33, s78
	v_lshl_add_u64 v[238:239], s[12:13], 0, v[156:157]
	s_mov_b32 m0, s33
	ds_read_b128 v[190:193], v221 offset:16384
	ds_read_b128 v[194:197], v221 offset:17408
	ds_read_b128 v[198:201], v221 offset:18432
	ds_read_b128 v[202:205], v221 offset:19456
	ds_read_b128 v[222:225], v221 offset:20480
	ds_read_b128 v[226:229], v221 offset:21504
	ds_read_b128 v[230:233], v221 offset:22528
	ds_read_b128 v[234:237], v221 offset:23552
	global_load_lds_dwordx4 v[238:239], off
	s_add_i32 m0, s33, 0x2000
	s_add_u32 s42, s12, 0x10000
	v_lshl_add_u64 v[240:241], s[12:13], 0, v[160:161]
	s_addc_u32 s43, s13, 0
	s_add_i32 s33, s35, s78
	global_load_lds_dwordx4 v[240:241], off
	v_lshl_add_u64 v[242:243], s[42:43], 0, v[156:157]
	s_mov_b32 m0, s33
	v_lshl_add_u64 v[244:245], s[14:15], 0, v[158:159]
	global_load_lds_dwordx4 v[242:243], off
	v_lshl_add_u64 v[242:243], s[42:43], 0, v[160:161]
	s_add_i32 m0, s33, 0x2000
	s_nop 0
	global_load_lds_dwordx4 v[242:243], off
	v_lshl_add_u64 v[242:243], s[14:15], 0, v[154:155]
	s_mov_b32 m0, s79
	s_nop 0
	global_load_lds_dwordx4 v[242:243], off
	s_mov_b32 m0, s81
	s_nop 0
	global_load_lds_dwordx4 v[244:245], off
	s_waitcnt vmcnt(8)
	s_waitcnt lgkmcnt(0)
	s_barrier
	s_setprio 1
	s_waitcnt lgkmcnt(0)
	v_mfma_f32_16x16x32_bf16 v[68:71], v[0:3], v[190:193], 0
	v_mfma_f32_16x16x32_bf16 v[64:67], v[138:141], v[190:193], 0
	v_mfma_f32_16x16x32_bf16 v[52:55], v[0:3], v[198:201], 0
	v_mfma_f32_16x16x32_bf16 v[48:51], v[138:141], v[198:201], 0
	v_mfma_f32_16x16x32_bf16 v[36:39], v[0:3], v[222:225], 0
	v_mfma_f32_16x16x32_bf16 v[32:35], v[138:141], v[222:225], 0
	v_mfma_f32_16x16x32_bf16 v[0:3], v[0:3], v[230:233], 0
	v_mfma_f32_16x16x32_bf16 v[68:71], v[4:7], v[194:197], v[68:71]
	v_mfma_f32_16x16x32_bf16 v[64:67], v[142:145], v[194:197], v[64:67]
	v_mfma_f32_16x16x32_bf16 v[52:55], v[4:7], v[202:205], v[52:55]
	v_mfma_f32_16x16x32_bf16 v[48:51], v[142:145], v[202:205], v[48:51]
	v_mfma_f32_16x16x32_bf16 v[36:39], v[4:7], v[226:229], v[36:39]
	v_mfma_f32_16x16x32_bf16 v[32:35], v[142:145], v[226:229], v[32:35]
	v_mfma_f32_16x16x32_bf16 v[0:3], v[4:7], v[234:237], v[0:3]
	v_mfma_f32_16x16x32_bf16 v[4:7], v[138:141], v[230:233], 0
	v_mfma_f32_16x16x32_bf16 v[4:7], v[142:145], v[234:237], v[4:7]
	s_setprio 0
	s_setprio 1
	v_mfma_f32_16x16x32_bf16 v[16:19], v[146:149], v[190:193], 0
	v_mfma_f32_16x16x32_bf16 v[60:63], v[150:153], v[194:197], v[16:19]
	v_mfma_f32_16x16x32_bf16 v[16:19], v[182:185], v[190:193], 0
	v_mfma_f32_16x16x32_bf16 v[56:59], v[186:189], v[194:197], v[16:19]
	v_mfma_f32_16x16x32_bf16 v[16:19], v[146:149], v[198:201], 0
	v_mfma_f32_16x16x32_bf16 v[44:47], v[150:153], v[202:205], v[16:19]
	v_mfma_f32_16x16x32_bf16 v[16:19], v[182:185], v[198:201], 0
	v_mfma_f32_16x16x32_bf16 v[40:43], v[186:189], v[202:205], v[16:19]
	v_mfma_f32_16x16x32_bf16 v[16:19], v[146:149], v[222:225], 0
	v_mfma_f32_16x16x32_bf16 v[28:31], v[150:153], v[226:229], v[16:19]
	v_mfma_f32_16x16x32_bf16 v[16:19], v[182:185], v[222:225], 0
	v_mfma_f32_16x16x32_bf16 v[12:15], v[146:149], v[230:233], 0
	v_mfma_f32_16x16x32_bf16 v[8:11], v[182:185], v[230:233], 0
	v_mfma_f32_16x16x32_bf16 v[24:27], v[186:189], v[226:229], v[16:19]
	v_mfma_f32_16x16x32_bf16 v[12:15], v[150:153], v[234:237], v[12:15]
	v_mfma_f32_16x16x32_bf16 v[8:11], v[186:189], v[234:237], v[8:11]
	s_setprio 0
	s_barrier
	v_add_u32_e32 v96, s67, v165
	s_add_i32 s33, 0, 0x1c000
	ds_read_b128 v[16:19], v96
	ds_read_b128 v[20:23], v96 offset:1024
	ds_read_b128 v[138:141], v96 offset:2048
	ds_read_b128 v[142:145], v96 offset:3072
	v_add_u32_e32 v96, s33, v165
	ds_read_b128 v[146:149], v96
	ds_read_b128 v[150:153], v96 offset:1024
	ds_read_b128 v[182:185], v96 offset:2048
	ds_read_b128 v[186:189], v96 offset:3072
	s_add_u32 s14, s14, 0x40000
	s_addc_u32 s15, s15, 0
	s_mov_b32 m0, s92
	v_lshl_add_u64 v[246:247], s[14:15], 0, v[154:155]
	ds_read_b128 v[190:193], v221 offset:32768
	ds_read_b128 v[194:197], v221 offset:33792
	ds_read_b128 v[198:201], v221 offset:34816
	ds_read_b128 v[202:205], v221 offset:35840
	ds_read_b128 v[222:225], v221 offset:36864
	ds_read_b128 v[226:229], v221 offset:37888
	ds_read_b128 v[230:233], v221 offset:38912
	ds_read_b128 v[234:237], v221 offset:39936
	global_load_lds_dwordx4 v[246:247], off
	v_lshl_add_u64 v[246:247], s[14:15], 0, v[158:159]
	s_mov_b32 m0, s93
	s_nop 0
	global_load_lds_dwordx4 v[246:247], off
	s_waitcnt vmcnt(8)
	s_waitcnt lgkmcnt(0)
	s_barrier
	s_setprio 1
	s_waitcnt lgkmcnt(0)
	v_mfma_f32_16x16x32_bf16 v[134:137], v[16:19], v[190:193], v[134:137]
	v_mfma_f32_16x16x32_bf16 v[130:133], v[138:141], v[190:193], v[130:133]
	v_mfma_f32_16x16x32_bf16 v[118:121], v[16:19], v[198:201], v[118:121]
	v_mfma_f32_16x16x32_bf16 v[114:117], v[138:141], v[198:201], v[114:117]
	v_mfma_f32_16x16x32_bf16 v[102:105], v[16:19], v[222:225], v[102:105]
	v_mfma_f32_16x16x32_bf16 v[98:101], v[138:141], v[222:225], v[98:101]
	v_mfma_f32_16x16x32_bf16 v[84:87], v[16:19], v[230:233], v[84:87]
	v_mfma_f32_16x16x32_bf16 v[80:83], v[138:141], v[230:233], v[80:83]
	v_mfma_f32_16x16x32_bf16 v[134:137], v[20:23], v[194:197], v[134:137]
	v_mfma_f32_16x16x32_bf16 v[130:133], v[142:145], v[194:197], v[130:133]
	v_mfma_f32_16x16x32_bf16 v[118:121], v[20:23], v[202:205], v[118:121]
	v_mfma_f32_16x16x32_bf16 v[114:117], v[142:145], v[202:205], v[114:117]
	v_mfma_f32_16x16x32_bf16 v[102:105], v[20:23], v[226:229], v[102:105]
	v_mfma_f32_16x16x32_bf16 v[98:101], v[142:145], v[226:229], v[98:101]
	v_mfma_f32_16x16x32_bf16 v[84:87], v[20:23], v[234:237], v[84:87]
	v_mfma_f32_16x16x32_bf16 v[80:83], v[142:145], v[234:237], v[80:83]
	s_setprio 0
	s_setprio 1
	v_mfma_f32_16x16x32_bf16 v[126:129], v[146:149], v[190:193], v[126:129]
	v_mfma_f32_16x16x32_bf16 v[122:125], v[182:185], v[190:193], v[122:125]
	v_mfma_f32_16x16x32_bf16 v[110:113], v[146:149], v[198:201], v[110:113]
	v_mfma_f32_16x16x32_bf16 v[106:109], v[182:185], v[198:201], v[106:109]
	v_mfma_f32_16x16x32_bf16 v[92:95], v[146:149], v[222:225], v[92:95]
	v_mfma_f32_16x16x32_bf16 v[88:91], v[182:185], v[222:225], v[88:91]
	v_mfma_f32_16x16x32_bf16 v[76:79], v[146:149], v[230:233], v[76:79]
	v_mfma_f32_16x16x32_bf16 v[72:75], v[182:185], v[230:233], v[72:75]
	v_mfma_f32_16x16x32_bf16 v[126:129], v[150:153], v[194:197], v[126:129]
	v_mfma_f32_16x16x32_bf16 v[122:125], v[186:189], v[194:197], v[122:125]
	v_mfma_f32_16x16x32_bf16 v[110:113], v[150:153], v[202:205], v[110:113]
	v_mfma_f32_16x16x32_bf16 v[106:109], v[186:189], v[202:205], v[106:109]
	v_mfma_f32_16x16x32_bf16 v[92:95], v[150:153], v[226:229], v[92:95]
	v_mfma_f32_16x16x32_bf16 v[88:91], v[186:189], v[226:229], v[88:91]
	v_mfma_f32_16x16x32_bf16 v[76:79], v[150:153], v[234:237], v[76:79]
	v_mfma_f32_16x16x32_bf16 v[72:75], v[186:189], v[234:237], v[72:75]
	s_setprio 0
	s_barrier
	s_add_i32 s14, s67, s78
	v_lshl_add_u64 v[238:239], v[238:239], 0, s[62:63]
	s_mov_b32 m0, s14
	ds_read_b128 v[190:193], v221 offset:49152
	ds_read_b128 v[194:197], v221 offset:50176
	ds_read_b128 v[198:201], v221 offset:51200
	ds_read_b128 v[202:205], v221 offset:52224
	ds_read_b128 v[222:225], v221 offset:53248
	ds_read_b128 v[226:229], v221 offset:54272
	ds_read_b128 v[230:233], v221 offset:55296
	ds_read_b128 v[234:237], v221 offset:56320
	global_load_lds_dwordx4 v[238:239], off
	s_add_i32 m0, s14, 0x2000
	s_add_u32 s12, s12, 0x10080
	v_lshl_add_u64 v[238:239], v[240:241], 0, s[62:63]
	s_addc_u32 s13, s13, 0
	s_add_i32 s14, s33, s78
	global_load_lds_dwordx4 v[238:239], off
	v_lshl_add_u64 v[238:239], s[12:13], 0, v[156:157]
	s_mov_b32 m0, s14
	s_nop 0
	global_load_lds_dwordx4 v[238:239], off
	v_lshl_add_u64 v[238:239], s[12:13], 0, v[160:161]
	s_add_i32 m0, s14, 0x2000
	s_nop 0
	global_load_lds_dwordx4 v[238:239], off
	v_lshl_add_u64 v[238:239], v[242:243], 0, s[62:63]
	s_mov_b32 m0, s21
	s_nop 0
	global_load_lds_dwordx4 v[238:239], off
	v_lshl_add_u64 v[238:239], v[244:245], 0, s[62:63]
	s_mov_b32 m0, s61
	s_nop 0
	global_load_lds_dwordx4 v[238:239], off
	s_waitcnt vmcnt(8)
	s_waitcnt lgkmcnt(0)
	s_barrier
	s_setprio 1
	s_waitcnt lgkmcnt(0)
	v_mfma_f32_16x16x32_bf16 v[68:71], v[16:19], v[190:193], v[68:71]
	v_mfma_f32_16x16x32_bf16 v[52:55], v[16:19], v[198:201], v[52:55]
	v_mfma_f32_16x16x32_bf16 v[36:39], v[16:19], v[222:225], v[36:39]
	v_mfma_f32_16x16x32_bf16 v[0:3], v[16:19], v[230:233], v[0:3]
	v_mfma_f32_16x16x32_bf16 v[68:71], v[20:23], v[194:197], v[68:71]
	v_mfma_f32_16x16x32_bf16 v[64:67], v[138:141], v[190:193], v[64:67]
	v_mfma_f32_16x16x32_bf16 v[52:55], v[20:23], v[202:205], v[52:55]
	v_mfma_f32_16x16x32_bf16 v[48:51], v[138:141], v[198:201], v[48:51]
	v_mfma_f32_16x16x32_bf16 v[36:39], v[20:23], v[226:229], v[36:39]
	v_mfma_f32_16x16x32_bf16 v[32:35], v[138:141], v[222:225], v[32:35]
	v_mfma_f32_16x16x32_bf16 v[20:23], v[20:23], v[234:237], v[0:3]
	v_mfma_f32_16x16x32_bf16 v[0:3], v[138:141], v[230:233], v[4:7]
	v_mfma_f32_16x16x32_bf16 v[64:67], v[142:145], v[194:197], v[64:67]
	v_mfma_f32_16x16x32_bf16 v[48:51], v[142:145], v[202:205], v[48:51]
	v_mfma_f32_16x16x32_bf16 v[32:35], v[142:145], v[226:229], v[32:35]
	v_mfma_f32_16x16x32_bf16 v[16:19], v[142:145], v[234:237], v[0:3]
	s_setprio 0
	s_setprio 1
	v_mfma_f32_16x16x32_bf16 v[0:3], v[146:149], v[190:193], v[60:63]
	v_mfma_f32_16x16x32_bf16 v[60:63], v[150:153], v[194:197], v[0:3]
	v_mfma_f32_16x16x32_bf16 v[0:3], v[182:185], v[190:193], v[56:59]
	v_mfma_f32_16x16x32_bf16 v[56:59], v[186:189], v[194:197], v[0:3]
	v_mfma_f32_16x16x32_bf16 v[0:3], v[146:149], v[198:201], v[44:47]
	v_mfma_f32_16x16x32_bf16 v[44:47], v[150:153], v[202:205], v[0:3]
	v_mfma_f32_16x16x32_bf16 v[0:3], v[182:185], v[198:201], v[40:43]
	v_mfma_f32_16x16x32_bf16 v[40:43], v[186:189], v[202:205], v[0:3]
	v_mfma_f32_16x16x32_bf16 v[0:3], v[146:149], v[222:225], v[28:31]
	v_mfma_f32_16x16x32_bf16 v[28:31], v[150:153], v[226:229], v[0:3]
	v_mfma_f32_16x16x32_bf16 v[0:3], v[182:185], v[222:225], v[24:27]
	v_mfma_f32_16x16x32_bf16 v[24:27], v[186:189], v[226:229], v[0:3]
	v_mfma_f32_16x16x32_bf16 v[0:3], v[146:149], v[230:233], v[12:15]
	v_mfma_f32_16x16x32_bf16 v[12:15], v[150:153], v[234:237], v[0:3]
	v_mfma_f32_16x16x32_bf16 v[0:3], v[182:185], v[230:233], v[8:11]
	v_mfma_f32_16x16x32_bf16 v[8:11], v[186:189], v[234:237], v[0:3]
	s_setprio 0
	s_barrier
	s_add_i32 s27, s27, 2
	s_add_u32 s4, s4, 0x100
	s_addc_u32 s5, s5, 0
	s_add_u32 s19, s19, 0x100
	s_addc_u32 s26, s26, 0
	.p2align 6
